# attention PV: softmax row-sum partials with v_pk_add_f32 (pair accumulator) instead of two scalar add chains
# speedup vs baseline: 1.0002x; 1.0002x over previous
.LBB0_540:
	v_exp_f32_e32 v82, v82
	v_exp_f32_e32 v83, v83
	v_exp_f32_e32 v84, v84
	v_exp_f32_e32 v85, v85
	ds_read_b64_tr_b16 v[240:241], v207 offset:22528
	ds_read_b64_tr_b16 v[242:243], v207 offset:25088
	ds_read_b64_tr_b16 v[244:245], v207 offset:22592
	ds_read_b64_tr_b16 v[246:247], v207 offset:25152
	ds_read_b64_tr_b16 v[248:249], v207 offset:22656
	ds_read_b64_tr_b16 v[250:251], v207 offset:25216
	ds_read_b64_tr_b16 v[252:253], v207 offset:22720
	ds_read_b64_tr_b16 v[254:255], v207 offset:25280
	v_exp_f32_e32 v86, v86
	v_exp_f32_e32 v87, v87
	v_exp_f32_e32 v88, v88
	v_exp_f32_e32 v89, v89
	v_cvt_pk_bf16_f32 v224, v82, v83
	v_cvt_pk_bf16_f32 v225, v84, v85
	v_cvt_pk_bf16_f32 v226, v86, v87
	v_cvt_pk_bf16_f32 v227, v88, v89
	s_waitcnt lgkmcnt(14)
	v_mfma_f32_32x32x16_bf16 v[66:81], v[12:15], v[224:227], v[66:81]
	v_exp_f32_e32 v90, v90
	v_exp_f32_e32 v91, v91
	v_pk_add_f32 v[16:17], v[82:83], v[84:85]
	ds_read_b64_tr_b16 v[12:13], v207 offset:27648
	ds_read_b64_tr_b16 v[14:15], v207 offset:30208
	s_waitcnt lgkmcnt(14)
	v_mfma_f32_32x32x16_bf16 v[50:65], v[8:11], v[224:227], v[50:65]
	v_exp_f32_e32 v92, v92
	v_exp_f32_e32 v93, v93
	v_cvt_pk_bf16_f32 v228, v90, v91
	v_pk_add_f32 v[16:17], v[16:17], v[86:87]
	ds_read_b64_tr_b16 v[8:9], v207 offset:27712
	ds_read_b64_tr_b16 v[10:11], v207 offset:30272
	s_waitcnt lgkmcnt(14)
	v_mfma_f32_32x32x16_bf16 v[34:49], v[162:165], v[224:227], v[34:49]
	v_exp_f32_e32 v94, v94
	v_exp_f32_e32 v95, v95
	v_cvt_pk_bf16_f32 v229, v92, v93
	v_pk_add_f32 v[16:17], v[16:17], v[88:89]
	ds_read_b64_tr_b16 v[162:163], v207 offset:27776
	ds_read_b64_tr_b16 v[164:165], v207 offset:30336
	s_waitcnt lgkmcnt(14)
	v_mfma_f32_32x32x16_bf16 v[18:33], v[4:7], v[224:227], v[18:33]
	v_exp_f32_e32 v96, v96
	v_exp_f32_e32 v97, v97
	v_cvt_pk_bf16_f32 v230, v94, v95
	v_cvt_pk_bf16_f32 v231, v96, v97
	ds_read_b64_tr_b16 v[4:5], v207 offset:27840
	ds_read_b64_tr_b16 v[6:7], v207 offset:30400
	s_waitcnt lgkmcnt(14)
	v_mfma_f32_32x32x16_bf16 v[66:81], v[240:243], v[228:231], v[66:81]
	v_exp_f32_e32 v98, v98
	v_exp_f32_e32 v99, v99
	v_pk_add_f32 v[16:17], v[16:17], v[90:91]
	ds_read_b64_tr_b16 v[240:241], v207 offset:32768
	ds_read_b64_tr_b16 v[242:243], v207 offset:35328
	s_waitcnt lgkmcnt(14)
	v_mfma_f32_32x32x16_bf16 v[50:65], v[244:247], v[228:231], v[50:65]
	v_exp_f32_e32 v100, v100
	v_exp_f32_e32 v101, v101
	v_cvt_pk_bf16_f32 v232, v98, v99
	v_pk_add_f32 v[16:17], v[16:17], v[92:93]
	ds_read_b64_tr_b16 v[244:245], v207 offset:32832
	ds_read_b64_tr_b16 v[246:247], v207 offset:35392
	s_waitcnt lgkmcnt(14)
	v_mfma_f32_32x32x16_bf16 v[34:49], v[248:251], v[228:231], v[34:49]
	v_exp_f32_e32 v102, v102
	v_exp_f32_e32 v103, v103
	v_cvt_pk_bf16_f32 v233, v100, v101
	v_pk_add_f32 v[16:17], v[16:17], v[94:95]
	ds_read_b64_tr_b16 v[248:249], v207 offset:32896
	ds_read_b64_tr_b16 v[250:251], v207 offset:35456
	s_waitcnt lgkmcnt(14)
	v_mfma_f32_32x32x16_bf16 v[18:33], v[252:255], v[228:231], v[18:33]
	v_exp_f32_e32 v104, v104
	v_exp_f32_e32 v105, v105
	v_cvt_pk_bf16_f32 v234, v102, v103
	v_cvt_pk_bf16_f32 v235, v104, v105
	v_pk_add_f32 v[16:17], v[16:17], v[96:97]
	ds_read_b64_tr_b16 v[252:253], v207 offset:32960
	ds_read_b64_tr_b16 v[254:255], v207 offset:35520
	s_waitcnt lgkmcnt(14)
	v_mfma_f32_32x32x16_bf16 v[66:81], v[12:15], v[232:235], v[66:81]
	s_mov_b64 s[58:59], 0
	v_exp_f32_e32 v106, v106
	v_exp_f32_e32 v107, v107
	v_pk_add_f32 v[16:17], v[16:17], v[98:99]
	s_waitcnt lgkmcnt(12)
	v_mfma_f32_32x32x16_bf16 v[50:65], v[8:11], v[232:235], v[50:65]
	v_exp_f32_e32 v108, v108
	v_exp_f32_e32 v109, v109
	v_cvt_pk_bf16_f32 v236, v106, v107
	v_pk_add_f32 v[16:17], v[16:17], v[100:101]
	s_waitcnt lgkmcnt(10)
	v_mfma_f32_32x32x16_bf16 v[34:49], v[162:165], v[232:235], v[34:49]
	v_exp_f32_e32 v110, v110
	v_exp_f32_e32 v111, v111
	v_cvt_pk_bf16_f32 v237, v108, v109
	v_pk_add_f32 v[16:17], v[16:17], v[102:103]
	s_waitcnt lgkmcnt(8)
	v_mfma_f32_32x32x16_bf16 v[18:33], v[4:7], v[232:235], v[18:33]
	v_exp_f32_e32 v112, v112
	v_exp_f32_e32 v113, v113
	v_cvt_pk_bf16_f32 v238, v110, v111
	v_cvt_pk_bf16_f32 v239, v112, v113
	v_pk_add_f32 v[16:17], v[16:17], v[104:105]
	s_waitcnt lgkmcnt(6)
	v_mfma_f32_32x32x16_bf16 v[66:81], v[240:243], v[236:239], v[66:81]
	v_pk_add_f32 v[16:17], v[16:17], v[106:107]
	s_waitcnt lgkmcnt(4)
	v_mfma_f32_32x32x16_bf16 v[50:65], v[244:247], v[236:239], v[50:65]
	v_pk_add_f32 v[16:17], v[16:17], v[108:109]
	s_waitcnt lgkmcnt(2)
	v_mfma_f32_32x32x16_bf16 v[34:49], v[248:251], v[236:239], v[34:49]
	v_pk_add_f32 v[16:17], v[16:17], v[110:111]
	s_waitcnt lgkmcnt(0)
	v_mfma_f32_32x32x16_bf16 v[18:33], v[252:255], v[236:239], v[18:33]
	v_pk_add_f32 v[16:17], v[16:17], v[112:113]
	s_nop 0
	v_add_f32_e32 v2, v16, v17
	v_add_f32_e32 v168, v168, v2

.LBB0_556:
	s_nop 2
	v_exp_f32_e32 v82, v82
	v_exp_f32_e32 v83, v83
	v_exp_f32_e32 v84, v84
	v_exp_f32_e32 v85, v85
	ds_read_b64_tr_b16 v[240:241], v210 offset:5120
	ds_read_b64_tr_b16 v[242:243], v210 offset:7680
	ds_read_b64_tr_b16 v[244:245], v210 offset:5184
	ds_read_b64_tr_b16 v[246:247], v210 offset:7744
	ds_read_b64_tr_b16 v[248:249], v210 offset:5248
	ds_read_b64_tr_b16 v[250:251], v210 offset:7808
	ds_read_b64_tr_b16 v[252:253], v210 offset:5312
	ds_read_b64_tr_b16 v[254:255], v210 offset:7872
	v_exp_f32_e32 v86, v86
	v_exp_f32_e32 v87, v87
	v_exp_f32_e32 v88, v88
	v_exp_f32_e32 v89, v89
	v_cvt_pk_bf16_f32 v224, v82, v83
	v_cvt_pk_bf16_f32 v225, v84, v85
	v_cvt_pk_bf16_f32 v226, v86, v87
	v_cvt_pk_bf16_f32 v227, v88, v89
	s_waitcnt lgkmcnt(14)
	v_mfma_f32_32x32x16_bf16 v[66:81], v[162:165], v[224:227], v[66:81]
	v_exp_f32_e32 v90, v90
	v_exp_f32_e32 v91, v91
	v_pk_add_f32 v[16:17], v[82:83], v[84:85]
	ds_read_b64_tr_b16 v[162:163], v210 offset:10240
	ds_read_b64_tr_b16 v[164:165], v210 offset:12800
	s_waitcnt lgkmcnt(14)
	v_mfma_f32_32x32x16_bf16 v[50:65], v[12:15], v[224:227], v[50:65]
	v_exp_f32_e32 v92, v92
	v_exp_f32_e32 v93, v93
	v_cvt_pk_bf16_f32 v228, v90, v91
	v_pk_add_f32 v[16:17], v[16:17], v[86:87]
	ds_read_b64_tr_b16 v[12:13], v210 offset:10304
	ds_read_b64_tr_b16 v[14:15], v210 offset:12864
	s_waitcnt lgkmcnt(14)
	v_mfma_f32_32x32x16_bf16 v[34:49], v[8:11], v[224:227], v[34:49]
	v_exp_f32_e32 v94, v94
	v_exp_f32_e32 v95, v95
	v_cvt_pk_bf16_f32 v229, v92, v93
	v_pk_add_f32 v[16:17], v[16:17], v[88:89]
	ds_read_b64_tr_b16 v[8:9], v210 offset:10368
	ds_read_b64_tr_b16 v[10:11], v210 offset:12928
	s_waitcnt lgkmcnt(14)
	v_mfma_f32_32x32x16_bf16 v[18:33], v[4:7], v[224:227], v[18:33]
	v_exp_f32_e32 v96, v96
	v_exp_f32_e32 v97, v97
	v_cvt_pk_bf16_f32 v230, v94, v95
	v_cvt_pk_bf16_f32 v231, v96, v97
	ds_read_b64_tr_b16 v[4:5], v210 offset:10432
	ds_read_b64_tr_b16 v[6:7], v210 offset:12992
	s_waitcnt lgkmcnt(14)
	v_mfma_f32_32x32x16_bf16 v[66:81], v[240:243], v[228:231], v[66:81]
	v_exp_f32_e32 v98, v98
	v_exp_f32_e32 v99, v99
	v_pk_add_f32 v[16:17], v[16:17], v[90:91]
	ds_read_b64_tr_b16 v[240:241], v210 offset:15360
	ds_read_b64_tr_b16 v[242:243], v210 offset:17920
	s_waitcnt lgkmcnt(14)
	v_mfma_f32_32x32x16_bf16 v[50:65], v[244:247], v[228:231], v[50:65]
	v_exp_f32_e32 v100, v100
	v_exp_f32_e32 v101, v101
	v_cvt_pk_bf16_f32 v232, v98, v99
	v_pk_add_f32 v[16:17], v[16:17], v[92:93]
	ds_read_b64_tr_b16 v[244:245], v210 offset:15424
	ds_read_b64_tr_b16 v[246:247], v210 offset:17984
	s_waitcnt lgkmcnt(14)
	v_mfma_f32_32x32x16_bf16 v[34:49], v[248:251], v[228:231], v[34:49]
	v_exp_f32_e32 v102, v102
	v_exp_f32_e32 v103, v103
	v_cvt_pk_bf16_f32 v233, v100, v101
	v_pk_add_f32 v[16:17], v[16:17], v[94:95]
	ds_read_b64_tr_b16 v[248:249], v210 offset:15488
	ds_read_b64_tr_b16 v[250:251], v210 offset:18048
	s_waitcnt lgkmcnt(14)
	v_mfma_f32_32x32x16_bf16 v[18:33], v[252:255], v[228:231], v[18:33]
	v_exp_f32_e32 v104, v104
	v_exp_f32_e32 v105, v105
	v_cvt_pk_bf16_f32 v234, v102, v103
	v_cvt_pk_bf16_f32 v235, v104, v105
	v_pk_add_f32 v[16:17], v[16:17], v[96:97]
	ds_read_b64_tr_b16 v[252:253], v210 offset:15552
	ds_read_b64_tr_b16 v[254:255], v210 offset:18112
	s_waitcnt lgkmcnt(14)
	v_mfma_f32_32x32x16_bf16 v[66:81], v[162:165], v[232:235], v[66:81]
	s_mov_b64 s[58:59], 0
	v_exp_f32_e32 v106, v106
	v_exp_f32_e32 v107, v107
	v_pk_add_f32 v[16:17], v[16:17], v[98:99]
	s_waitcnt lgkmcnt(12)
	v_mfma_f32_32x32x16_bf16 v[50:65], v[12:15], v[232:235], v[50:65]
	v_exp_f32_e32 v108, v108
	v_exp_f32_e32 v109, v109
	v_cvt_pk_bf16_f32 v236, v106, v107
	v_pk_add_f32 v[16:17], v[16:17], v[100:101]
	s_waitcnt lgkmcnt(10)
	v_mfma_f32_32x32x16_bf16 v[34:49], v[8:11], v[232:235], v[34:49]
	v_exp_f32_e32 v110, v110
	v_exp_f32_e32 v111, v111
	v_cvt_pk_bf16_f32 v237, v108, v109
	v_pk_add_f32 v[16:17], v[16:17], v[102:103]
	s_waitcnt lgkmcnt(8)
	v_mfma_f32_32x32x16_bf16 v[18:33], v[4:7], v[232:235], v[18:33]
	v_exp_f32_e32 v112, v112
	v_exp_f32_e32 v113, v113
	v_cvt_pk_bf16_f32 v238, v110, v111
	v_cvt_pk_bf16_f32 v239, v112, v113
	v_pk_add_f32 v[16:17], v[16:17], v[104:105]
	s_waitcnt lgkmcnt(6)
	v_mfma_f32_32x32x16_bf16 v[66:81], v[240:243], v[236:239], v[66:81]
	v_pk_add_f32 v[16:17], v[16:17], v[106:107]
	s_waitcnt lgkmcnt(4)
	v_mfma_f32_32x32x16_bf16 v[50:65], v[244:247], v[236:239], v[50:65]
	v_pk_add_f32 v[16:17], v[16:17], v[108:109]
	s_waitcnt lgkmcnt(2)
	v_mfma_f32_32x32x16_bf16 v[34:49], v[248:251], v[236:239], v[34:49]
	v_pk_add_f32 v[16:17], v[16:17], v[110:111]
	s_waitcnt lgkmcnt(0)
	v_mfma_f32_32x32x16_bf16 v[18:33], v[252:255], v[236:239], v[18:33]
	v_pk_add_f32 v[16:17], v[16:17], v[112:113]
	s_nop 0
	v_add_f32_e32 v2, v16, v17
	v_add_f32_e32 v168, v168, v2
	s_cmp_ge_i32 s85, s81
	s_cbranch_scc1 .LBB0_548
